# M2 + G_in/G_up K-loop LDS-DMA addressing rewritten to scalar bases (SADDR form, s_add instead of 16 v_lshl_add_u64 per 2 K-tiles per wave)
# speedup vs baseline: 1.0016x; 1.0016x over previous
; #define PG8_SB(B) __builtin_amdgcn_rcpf(1.f + expneg(B))
; #define PG8_SB(B) __builtin_amdgcn_rcpf(1.f + expneg(B))
; #define PG8_STAGE(bufoff, gbase, voff) do { _Pragma("unroll") for (int _i = 0; _i < 2; ++_i) \
;         __builtin_amdgcn_global_load_lds((const unsigned*)((const char*)(gbase) + (size_t)_i * qstep + (voff)[0]), (PG8_LAS unsigned*)(lds + (bufoff) + ldsw + _i * 8192), 16, 0, 0); } while (0)
; #define PG8_LDA(dst, b, h) do { _Pragma("unroll") for (int m = 0; m < 4; ++m) _Pragma("unroll") for (int k = 0; k < 2; ++k) dst[m][k] = *(const PG8_LAS bf16x8*)(lds + PG8_SA(b, h) + aoff + m * 2048 + k * 1024); } while (0)
; #define PG8_LDB(dst, b, h) do { _Pragma("unroll") for (int n = 0; n < 2; ++n) _Pragma("unroll") for (int k = 0; k < 2; ++k) dst[n][k] = *(const PG8_LAS bf16x8*)(lds + PG8_SB(b, h) + boff + n * 2048 + k * 1024); } while (0)
; #define PG8_WAIT_V89() do { if constexpr (SLIVER) PG8_WAIT_V(9); else PG8_WAIT_V(8); } while (0)
; #define PG8_WAIT_L(n) asm volatile("s_waitcnt lgkmcnt(" #n ")" ::: "memory")
; #define PG8_BAR __builtin_amdgcn_s_barrier()
; template <class Epi, class Sched, bool ALIGN_EPI = false, bool SP2 = false, bool SLIVER = false>
; __device__ __forceinline__ void gemm_phase(PG8_LAS unsigned char* lds, const Gemm g, const Sched& S, const Epi& E) {
;     ...
;             const bool last = (t == nt - 2);
;             const char* a1 = cA + (size_t)(t + 1) * kstep;
;             const char* a2 = last ? nA : cA + (size_t)(t + 2) * kstep; const char* b2 = last ? nB : cB + (size_t)(t + 2) * kstep;
;             const char* a3 = a2 + kstep; const char* b3 = b2 + kstep;
;             const char* s1 = cS + (size_t)(t + 1) * kstep; const char* s2 = last ? nS : cS + (size_t)(t + 2) * kstep;
;             if (last && has_next) S.a_ready(nxt);
;             if constexpr (SP2) {
;             PG8_LDB(B0, 0, 0); PG8_LDB(B1, 0, 1); PG8_SCHED; PG8_LDA(At, 0, 0); PG8_STAGE(PG8_SA(1, 1), a1 + hstep, voffA); PG8_STAGE_S(1, s1);
;             PG8_WAIT_V89(); PG8_WAIT_L(0); PG8_BAR; PG8_MMA(0, 0, At, B0); PG8_MMA(0, 1, At, B1); PG8_BAR; PG8_SCHED;
;             PG8_LDA(At, 0, 1); PG8_LDS_S(0); PG8_STAGE(PG8_SB(0, 0), b2, voffB); PG8_STAGE(PG8_SB(0, 1), b2 + hstep, voffB); PG8_STAGE(PG8_SA(0, 0), a2, voffA);
;             PG8_WAIT_V89(); PG8_WAIT_L(0); PG8_BAR; PG8_MMA(1, 0, At, B0); PG8_MMA(1, 1, At, B1); PG8_MMA_S(); PG8_BAR; PG8_SCHED;
.LBB0_153:
	s_add_u32 s62, s40, 0xfff80080
	s_addc_u32 s63, s41, -1
	s_add_i32 s77, 0, 0x10000
	s_cmp_eq_u32 s76, 28
	s_cselect_b32 s63, s12, s63
	s_cselect_b32 s62, s13, s62
	v_add_u32_e32 v144, s77, v145
	s_cselect_b32 s79, s66, s69
	s_cselect_b32 s78, s67, s68
	s_add_i32 s80, 0, 0x14000
	ds_read_b128 v[136:139], v144
	ds_read_b128 v[140:143], v144 offset:1024
	ds_read_b128 v[150:153], v144 offset:2048
	ds_read_b128 v[154:157], v144 offset:3072
	v_add_u32_e32 v144, s80, v145
	ds_read_b128 v[158:161], v144
	ds_read_b128 v[162:165], v144 offset:1024
	ds_read_b128 v[166:169], v144 offset:2048
	ds_read_b128 v[170:173], v144 offset:3072
	s_mov_b64 s[46:47], s[40:41]
	s_add_i32 m0, s91, 0xc000
	ds_read_b128 v[174:177], v149
	ds_read_b128 v[180:183], v149 offset:1024
	ds_read_b128 v[184:187], v149 offset:2048
	ds_read_b128 v[188:191], v149 offset:3072
	ds_read_b128 v[192:195], v149 offset:4096
	ds_read_b128 v[196:199], v149 offset:5120
	ds_read_b128 v[200:203], v149 offset:6144
	ds_read_b128 v[210:213], v149 offset:7168
	global_load_lds_dwordx4 v134, s[46:47]
	s_add_i32 m0, s91, 0xe000
	s_nop 0
	s_add_u32 s36, s46, 0x40000
	s_addc_u32 s37, s47, 0
	global_load_lds_dwordx4 v134, s[36:37]
	s_cmp_eq_u32 s76, s101
	s_cbranch_scc1 .Lgin_skipw0
	s_waitcnt vmcnt(8)
.Lgin_skipw0:
	s_waitcnt lgkmcnt(0)
	s_setprio 1
	s_barrier
	v_mfma_f32_16x16x32_bf16 v[126:129], v[136:139], v[174:177], v[126:129]
	v_mfma_f32_16x16x32_bf16 v[122:125], v[150:153], v[174:177], v[122:125]
	v_mfma_f32_16x16x32_bf16 v[114:117], v[136:139], v[184:187], v[114:117]
	v_mfma_f32_16x16x32_bf16 v[106:109], v[150:153], v[184:187], v[106:109]
	v_mfma_f32_16x16x32_bf16 v[98:101], v[136:139], v[192:195], v[98:101]
	v_mfma_f32_16x16x32_bf16 v[90:93], v[150:153], v[192:195], v[90:93]
	v_mfma_f32_16x16x32_bf16 v[82:85], v[136:139], v[200:203], v[82:85]
	v_mfma_f32_16x16x32_bf16 v[74:77], v[150:153], v[200:203], v[74:77]
	v_mfma_f32_16x16x32_bf16 v[126:129], v[140:143], v[180:183], v[126:129]
	v_mfma_f32_16x16x32_bf16 v[122:125], v[154:157], v[180:183], v[122:125]
	v_mfma_f32_16x16x32_bf16 v[114:117], v[140:143], v[188:191], v[114:117]
	v_mfma_f32_16x16x32_bf16 v[106:109], v[154:157], v[188:191], v[106:109]
	v_mfma_f32_16x16x32_bf16 v[98:101], v[140:143], v[196:199], v[98:101]
	v_mfma_f32_16x16x32_bf16 v[90:93], v[154:157], v[196:199], v[90:93]
	v_mfma_f32_16x16x32_bf16 v[82:85], v[140:143], v[210:213], v[82:85]
	v_mfma_f32_16x16x32_bf16 v[74:77], v[154:157], v[210:213], v[74:77]
	s_setprio 0
	s_setprio 1
	v_mfma_f32_16x16x32_bf16 v[118:121], v[158:161], v[174:177], v[118:121]
	v_mfma_f32_16x16x32_bf16 v[110:113], v[166:169], v[174:177], v[110:113]
	v_mfma_f32_16x16x32_bf16 v[102:105], v[158:161], v[184:187], v[102:105]
	v_mfma_f32_16x16x32_bf16 v[94:97], v[166:169], v[184:187], v[94:97]
	v_mfma_f32_16x16x32_bf16 v[86:89], v[158:161], v[192:195], v[86:89]
	v_mfma_f32_16x16x32_bf16 v[78:81], v[166:169], v[192:195], v[78:81]
	v_mfma_f32_16x16x32_bf16 v[70:73], v[158:161], v[200:203], v[70:73]
	v_mfma_f32_16x16x32_bf16 v[66:69], v[166:169], v[200:203], v[66:69]
	v_mfma_f32_16x16x32_bf16 v[118:121], v[162:165], v[180:183], v[118:121]
	v_mfma_f32_16x16x32_bf16 v[110:113], v[170:173], v[180:183], v[110:113]
	v_mfma_f32_16x16x32_bf16 v[102:105], v[162:165], v[188:191], v[102:105]
	v_mfma_f32_16x16x32_bf16 v[94:97], v[170:173], v[188:191], v[94:97]
	v_mfma_f32_16x16x32_bf16 v[86:89], v[162:165], v[196:199], v[86:89]
	v_mfma_f32_16x16x32_bf16 v[78:81], v[170:173], v[196:199], v[78:81]
	v_mfma_f32_16x16x32_bf16 v[70:73], v[162:165], v[210:213], v[70:73]
	v_mfma_f32_16x16x32_bf16 v[66:69], v[170:173], v[210:213], v[66:69]
	s_barrier
	s_setprio 0
	s_add_i32 s77, s77, s53
	s_mov_b32 m0, s77
	ds_read_b128 v[174:177], v149 offset:16384
	ds_read_b128 v[180:183], v149 offset:17408
	ds_read_b128 v[184:187], v149 offset:18432
	ds_read_b128 v[188:191], v149 offset:19456
	ds_read_b128 v[192:195], v149 offset:20480
	ds_read_b128 v[196:199], v149 offset:21504
	ds_read_b128 v[200:203], v149 offset:22528
	ds_read_b128 v[210:213], v149 offset:23552
	global_load_lds_dwordx4 v132, s[78:79]
	s_add_i32 m0, s77, 0x2000
	s_add_i32 s77, s80, s53
	s_add_u32 s58, s78, 0x40000
	s_addc_u32 s59, s79, 0
	global_load_lds_dwordx4 v132, s[58:59]
	s_mov_b32 m0, s77
	s_nop 0
	s_add_u32 s60, s78, 0x80000
	s_addc_u32 s61, s79, 0
	global_load_lds_dwordx4 v132, s[60:61]
	s_add_i32 m0, s77, 0x2000
	s_nop 0
	s_add_u32 s36, s78, 0xc0000
	s_addc_u32 s37, s79, 0
	global_load_lds_dwordx4 v132, s[36:37]
	s_mov_b64 s[46:47], s[62:63]
	s_mov_b32 m0, s91
	s_nop 0
	global_load_lds_dwordx4 v130, s[46:47]
	s_mov_b32 m0, s50
	s_nop 0
	s_add_u32 s58, s46, 0x40000
	s_addc_u32 s59, s47, 0
	global_load_lds_dwordx4 v130, s[58:59]
	s_cmp_eq_u32 s76, s101
	s_cbranch_scc1 .Lgin_skipw1
	s_waitcnt vmcnt(8)
; #define PG8_STAGE(bufoff, gbase, voff) do { _Pragma("unroll") for (int _i = 0; _i < 2; ++_i) \
;         __builtin_amdgcn_global_load_lds((const unsigned*)((const char*)(gbase) + (size_t)_i * qstep + (voff)[0]), (PG8_LAS unsigned*)(lds + (bufoff) + ldsw + _i * 8192), 16, 0, 0); } while (0)
; #define PG8_LDA(dst, b, h) do { _Pragma("unroll") for (int m = 0; m < 4; ++m) _Pragma("unroll") for (int k = 0; k < 2; ++k) dst[m][k] = *(const PG8_LAS bf16x8*)(lds + PG8_SA(b, h) + aoff + m * 2048 + k * 1024); } while (0)
; #define PG8_LDB(dst, b, h) do { _Pragma("unroll") for (int n = 0; n < 2; ++n) _Pragma("unroll") for (int k = 0; k < 2; ++k) dst[n][k] = *(const PG8_LAS bf16x8*)(lds + PG8_SB(b, h) + boff + n * 2048 + k * 1024); } while (0)
; #define PG8_MMA(ai, bj, At, Bt) do { __builtin_amdgcn_s_setprio(1); _Pragma("unroll") for (int m = 0; m < 4; ++m) _Pragma("unroll") for (int n = 0; n < 2; ++n) _Pragma("unroll") for (int k = 0; k < 2; ++k) \
;         acc[ai][bj][m][n] = __builtin_amdgcn_mfma_f32_16x16x32_bf16(Bt[n][k], At[m][k], acc[ai][bj][m][n], 0, 0, 0); __builtin_amdgcn_s_setprio(0); } while (0)
; #define PG8_WAIT_V89() do { if constexpr (SLIVER) PG8_WAIT_V(9); else PG8_WAIT_V(8); } while (0)
; #define PG8_STAGE_S(b, gbase) do { if constexpr (SLIVER) __builtin_amdgcn_global_load_lds((const unsigned*)((const char*)(gbase) + voffS), (PG8_LAS unsigned*)(lds + STAGE_BYTES + (b) * 2048 + wid * 256), 4, 0, 0); } while (0)
; #define PG8_WAIT_L(n) asm volatile("s_waitcnt lgkmcnt(" #n ")" ::: "memory")
; #define PG8_BAR __builtin_amdgcn_s_barrier()
; #define PG8_SCHED __builtin_amdgcn_sched_barrier(0)
; template <class Epi, class Sched, bool ALIGN_EPI = false, bool SP2 = false, bool SLIVER = false>
; __device__ __forceinline__ void gemm_phase(PG8_LAS unsigned char* lds, const Gemm g, const Sched& S, const Epi& E) {
;     ...
;             PG8_WAIT_V89(); PG8_WAIT_L(0); PG8_BAR; PG8_MMA(1, 0, At, B0); PG8_MMA(1, 1, At, B1); PG8_MMA_S(); PG8_BAR; PG8_SCHED;
;             PG8_LDB(B0, 1, 0); PG8_LDB(B1, 1, 1); PG8_SCHED; PG8_LDA(At, 1, 0); PG8_STAGE(PG8_SA(0, 1), a2 + hstep, voffA); PG8_STAGE_S(0, s2);
;             PG8_WAIT_V89(); PG8_WAIT_L(0); PG8_BAR; PG8_MMA(0, 0, At, B0); PG8_MMA(0, 1, At, B1); PG8_BAR; PG8_SCHED;
.Lgin_skipw1:
	s_waitcnt lgkmcnt(0)
	s_setprio 1
	s_barrier
	v_mfma_f32_16x16x32_bf16 v[62:65], v[136:139], v[174:177], v[62:65]
	v_mfma_f32_16x16x32_bf16 v[58:61], v[150:153], v[174:177], v[58:61]
	v_mfma_f32_16x16x32_bf16 v[50:53], v[136:139], v[184:187], v[50:53]
	v_mfma_f32_16x16x32_bf16 v[42:45], v[150:153], v[184:187], v[42:45]
	v_mfma_f32_16x16x32_bf16 v[34:37], v[136:139], v[192:195], v[34:37]
	v_mfma_f32_16x16x32_bf16 v[26:29], v[150:153], v[192:195], v[26:29]
	v_mfma_f32_16x16x32_bf16 v[18:21], v[136:139], v[200:203], v[18:21]
	v_mfma_f32_16x16x32_bf16 v[10:13], v[150:153], v[200:203], v[10:13]
	v_mfma_f32_16x16x32_bf16 v[62:65], v[140:143], v[180:183], v[62:65]
	v_mfma_f32_16x16x32_bf16 v[58:61], v[154:157], v[180:183], v[58:61]
	v_mfma_f32_16x16x32_bf16 v[50:53], v[140:143], v[188:191], v[50:53]
	v_mfma_f32_16x16x32_bf16 v[42:45], v[154:157], v[188:191], v[42:45]
	v_mfma_f32_16x16x32_bf16 v[34:37], v[140:143], v[196:199], v[34:37]
	v_mfma_f32_16x16x32_bf16 v[26:29], v[154:157], v[196:199], v[26:29]
	v_mfma_f32_16x16x32_bf16 v[18:21], v[140:143], v[210:213], v[18:21]
	v_mfma_f32_16x16x32_bf16 v[10:13], v[154:157], v[210:213], v[10:13]
	s_setprio 0
	s_setprio 1
	v_mfma_f32_16x16x32_bf16 v[54:57], v[158:161], v[174:177], v[54:57]
	v_mfma_f32_16x16x32_bf16 v[46:49], v[166:169], v[174:177], v[46:49]
	v_mfma_f32_16x16x32_bf16 v[38:41], v[158:161], v[184:187], v[38:41]
	v_mfma_f32_16x16x32_bf16 v[30:33], v[166:169], v[184:187], v[30:33]
	v_mfma_f32_16x16x32_bf16 v[22:25], v[158:161], v[192:195], v[22:25]
	v_mfma_f32_16x16x32_bf16 v[14:17], v[166:169], v[192:195], v[14:17]
	v_mfma_f32_16x16x32_bf16 v[6:9], v[158:161], v[200:203], v[6:9]
	v_mfma_f32_16x16x32_bf16 v[2:5], v[166:169], v[200:203], v[2:5]
	v_mfma_f32_16x16x32_bf16 v[54:57], v[162:165], v[180:183], v[54:57]
	v_mfma_f32_16x16x32_bf16 v[46:49], v[170:173], v[180:183], v[46:49]
	v_mfma_f32_16x16x32_bf16 v[38:41], v[162:165], v[188:191], v[38:41]
	v_mfma_f32_16x16x32_bf16 v[30:33], v[170:173], v[188:191], v[30:33]
	v_mfma_f32_16x16x32_bf16 v[22:25], v[162:165], v[196:199], v[22:25]
	v_mfma_f32_16x16x32_bf16 v[14:17], v[170:173], v[196:199], v[14:17]
	v_mfma_f32_16x16x32_bf16 v[6:9], v[162:165], v[210:213], v[6:9]
	v_mfma_f32_16x16x32_bf16 v[2:5], v[170:173], v[210:213], v[2:5]
	s_barrier
	s_setprio 0
	s_add_i32 s62, 0, 0x18000
	v_add_u32_e32 v144, s62, v145
	s_add_i32 s63, 0, 0x1c000
	ds_read_b128 v[136:139], v144
	ds_read_b128 v[140:143], v144 offset:1024
	ds_read_b128 v[150:153], v144 offset:2048
	ds_read_b128 v[154:157], v144 offset:3072
	v_add_u32_e32 v144, s63, v145
	ds_read_b128 v[158:161], v144
	ds_read_b128 v[162:165], v144 offset:1024
	ds_read_b128 v[166:169], v144 offset:2048
	ds_read_b128 v[170:173], v144 offset:3072
	s_mov_b32 m0, s51
	ds_read_b128 v[174:177], v149 offset:32768
	ds_read_b128 v[180:183], v149 offset:33792
	ds_read_b128 v[184:187], v149 offset:34816
	ds_read_b128 v[188:191], v149 offset:35840
	ds_read_b128 v[192:195], v149 offset:36864
	ds_read_b128 v[196:199], v149 offset:37888
	ds_read_b128 v[200:203], v149 offset:38912
	ds_read_b128 v[210:213], v149 offset:39936
	s_add_u32 s60, s46, 0x80000
	s_addc_u32 s61, s47, 0
	global_load_lds_dwordx4 v130, s[60:61]
	s_mov_b32 m0, s54
	s_nop 0
	s_add_u32 s36, s46, 0xc0000
	s_addc_u32 s37, s47, 0
	global_load_lds_dwordx4 v130, s[36:37]
	s_waitcnt vmcnt(8)
	s_waitcnt lgkmcnt(0)
	s_setprio 1
	s_barrier
	v_mfma_f32_16x16x32_bf16 v[126:129], v[136:139], v[174:177], v[126:129]
	v_mfma_f32_16x16x32_bf16 v[122:125], v[150:153], v[174:177], v[122:125]
	v_mfma_f32_16x16x32_bf16 v[114:117], v[136:139], v[184:187], v[114:117]
	v_mfma_f32_16x16x32_bf16 v[106:109], v[150:153], v[184:187], v[106:109]
	v_mfma_f32_16x16x32_bf16 v[98:101], v[136:139], v[192:195], v[98:101]
	v_mfma_f32_16x16x32_bf16 v[90:93], v[150:153], v[192:195], v[90:93]
	v_mfma_f32_16x16x32_bf16 v[82:85], v[136:139], v[200:203], v[82:85]
	v_mfma_f32_16x16x32_bf16 v[74:77], v[150:153], v[200:203], v[74:77]
	v_mfma_f32_16x16x32_bf16 v[126:129], v[140:143], v[180:183], v[126:129]
	v_mfma_f32_16x16x32_bf16 v[122:125], v[154:157], v[180:183], v[122:125]
	v_mfma_f32_16x16x32_bf16 v[114:117], v[140:143], v[188:191], v[114:117]
	v_mfma_f32_16x16x32_bf16 v[106:109], v[154:157], v[188:191], v[106:109]
	v_mfma_f32_16x16x32_bf16 v[98:101], v[140:143], v[196:199], v[98:101]
	v_mfma_f32_16x16x32_bf16 v[90:93], v[154:157], v[196:199], v[90:93]
	v_mfma_f32_16x16x32_bf16 v[82:85], v[140:143], v[210:213], v[82:85]
	v_mfma_f32_16x16x32_bf16 v[74:77], v[154:157], v[210:213], v[74:77]
	s_setprio 0
	s_setprio 1
	v_mfma_f32_16x16x32_bf16 v[118:121], v[158:161], v[174:177], v[118:121]
	v_mfma_f32_16x16x32_bf16 v[110:113], v[166:169], v[174:177], v[110:113]
	v_mfma_f32_16x16x32_bf16 v[102:105], v[158:161], v[184:187], v[102:105]
	v_mfma_f32_16x16x32_bf16 v[94:97], v[166:169], v[184:187], v[94:97]
	v_mfma_f32_16x16x32_bf16 v[86:89], v[158:161], v[192:195], v[86:89]
	v_mfma_f32_16x16x32_bf16 v[78:81], v[166:169], v[192:195], v[78:81]
	v_mfma_f32_16x16x32_bf16 v[70:73], v[158:161], v[200:203], v[70:73]
	v_mfma_f32_16x16x32_bf16 v[66:69], v[166:169], v[200:203], v[66:69]
	v_mfma_f32_16x16x32_bf16 v[118:121], v[162:165], v[180:183], v[118:121]
	v_mfma_f32_16x16x32_bf16 v[110:113], v[170:173], v[180:183], v[110:113]
	v_mfma_f32_16x16x32_bf16 v[102:105], v[162:165], v[188:191], v[102:105]
	v_mfma_f32_16x16x32_bf16 v[94:97], v[170:173], v[188:191], v[94:97]
	v_mfma_f32_16x16x32_bf16 v[86:89], v[162:165], v[196:199], v[86:89]
	v_mfma_f32_16x16x32_bf16 v[78:81], v[170:173], v[196:199], v[78:81]
	v_mfma_f32_16x16x32_bf16 v[70:73], v[162:165], v[210:213], v[70:73]
	v_mfma_f32_16x16x32_bf16 v[66:69], v[170:173], v[210:213], v[66:69]
	s_barrier
; #define PG8_SB(B) __builtin_amdgcn_rcpf(1.f + expneg(B))
; #define PG8_SB(B) __builtin_amdgcn_rcpf(1.f + expneg(B))
; #define PG8_STAGE(bufoff, gbase, voff) do { _Pragma("unroll") for (int _i = 0; _i < 2; ++_i) \
;         __builtin_amdgcn_global_load_lds((const unsigned*)((const char*)(gbase) + (size_t)_i * qstep + (voff)[0]), (PG8_LAS unsigned*)(lds + (bufoff) + ldsw + _i * 8192), 16, 0, 0); } while (0)
; #define PG8_LDA(dst, b, h) do { _Pragma("unroll") for (int m = 0; m < 4; ++m) _Pragma("unroll") for (int k = 0; k < 2; ++k) dst[m][k] = *(const PG8_LAS bf16x8*)(lds + PG8_SA(b, h) + aoff + m * 2048 + k * 1024); } while (0)
; #define PG8_MMA(ai, bj, At, Bt) do { __builtin_amdgcn_s_setprio(1); _Pragma("unroll") for (int m = 0; m < 4; ++m) _Pragma("unroll") for (int n = 0; n < 2; ++n) _Pragma("unroll") for (int k = 0; k < 2; ++k) \
;         acc[ai][bj][m][n] = __builtin_amdgcn_mfma_f32_16x16x32_bf16(Bt[n][k], At[m][k], acc[ai][bj][m][n], 0, 0, 0); __builtin_amdgcn_s_setprio(0); } while (0)
; #define PG8_WAIT_V89() do { if constexpr (SLIVER) PG8_WAIT_V(9); else PG8_WAIT_V(8); } while (0)
; #define PG8_LDS_S(b) do { if constexpr (SLIVER) { Sf[0] = *(const PG8_LAS bf16x8*)(lds + STAGE_BYTES + (b) * 2048 + soff0); Sf[1] = *(const PG8_LAS bf16x8*)(lds + STAGE_BYTES + (b) * 2048 + (soff0 ^ 64)); } } while (0)
; #define PG8_WAIT_L(n) asm volatile("s_waitcnt lgkmcnt(" #n ")" ::: "memory")
; #define PG8_BAR __builtin_amdgcn_s_barrier()
; #define PG8_SCHED __builtin_amdgcn_sched_barrier(0)
; template <class Epi, class Sched, bool ALIGN_EPI = false, bool SP2 = false, bool SLIVER = false>
; __device__ __forceinline__ void gemm_phase(PG8_LAS unsigned char* lds, const Gemm g, const Sched& S, const Epi& E) {
;     ...
;             PG8_LDA(At, 1, 1); PG8_LDS_S(1); PG8_STAGE(PG8_SB(1, 0), b3, voffB); PG8_STAGE(PG8_SB(1, 1), b3 + hstep, voffB); PG8_STAGE(PG8_SA(1, 0), a3, voffA);
;             PG8_WAIT_V89(); PG8_WAIT_L(0); PG8_BAR; PG8_MMA(1, 0, At, B0); PG8_MMA(1, 1, At, B1); PG8_MMA_S(); PG8_BAR; PG8_SCHED;
;     ...
;         if constexpr (ALIGN_EPI) { if (wr == 0) PG8_BAR; }
	s_setprio 0
	s_add_i32 s62, s62, s53
	s_mov_b32 m0, s62
	ds_read_b128 v[174:177], v149 offset:49152
	ds_read_b128 v[180:183], v149 offset:50176
	ds_read_b128 v[184:187], v149 offset:51200
	ds_read_b128 v[188:191], v149 offset:52224
	ds_read_b128 v[192:195], v149 offset:53248
	ds_read_b128 v[196:199], v149 offset:54272
	ds_read_b128 v[200:203], v149 offset:55296
	ds_read_b128 v[210:213], v149 offset:56320
	s_add_u32 s58, s78, 0x80
	s_addc_u32 s59, s79, 0
	global_load_lds_dwordx4 v132, s[58:59]
	s_add_i32 m0, s62, 0x2000
	s_add_i32 s62, s63, s53
	s_add_u32 s60, s78, 0x40080
	s_addc_u32 s61, s79, 0
	global_load_lds_dwordx4 v132, s[60:61]
	s_mov_b32 m0, s62
	s_add_u32 s36, s78, 0x80080
	s_addc_u32 s37, s79, 0
	global_load_lds_dwordx4 v132, s[36:37]
	s_add_i32 m0, s62, 0x2000
	s_nop 0
	s_add_u32 s58, s78, 0xc0080
	s_addc_u32 s59, s79, 0
	global_load_lds_dwordx4 v132, s[58:59]
	s_mov_b32 m0, s10
	s_nop 0
	s_add_u32 s60, s46, 0x80
	s_addc_u32 s61, s47, 0
	global_load_lds_dwordx4 v130, s[60:61]
	s_mov_b32 m0, s55
	s_nop 0
	s_add_u32 s36, s46, 0x40080
	s_addc_u32 s37, s47, 0
	global_load_lds_dwordx4 v130, s[36:37]
	s_waitcnt vmcnt(8)
	s_waitcnt lgkmcnt(0)
	s_setprio 1
	s_barrier
	v_mfma_f32_16x16x32_bf16 v[62:65], v[136:139], v[174:177], v[62:65]
	v_mfma_f32_16x16x32_bf16 v[58:61], v[150:153], v[174:177], v[58:61]
	v_mfma_f32_16x16x32_bf16 v[50:53], v[136:139], v[184:187], v[50:53]
	v_mfma_f32_16x16x32_bf16 v[42:45], v[150:153], v[184:187], v[42:45]
	v_mfma_f32_16x16x32_bf16 v[34:37], v[136:139], v[192:195], v[34:37]
	v_mfma_f32_16x16x32_bf16 v[26:29], v[150:153], v[192:195], v[26:29]
	v_mfma_f32_16x16x32_bf16 v[18:21], v[136:139], v[200:203], v[18:21]
	v_mfma_f32_16x16x32_bf16 v[10:13], v[150:153], v[200:203], v[10:13]
	v_mfma_f32_16x16x32_bf16 v[62:65], v[140:143], v[180:183], v[62:65]
	v_mfma_f32_16x16x32_bf16 v[58:61], v[154:157], v[180:183], v[58:61]
	v_mfma_f32_16x16x32_bf16 v[50:53], v[140:143], v[188:191], v[50:53]
	v_mfma_f32_16x16x32_bf16 v[42:45], v[154:157], v[188:191], v[42:45]
	v_mfma_f32_16x16x32_bf16 v[34:37], v[140:143], v[196:199], v[34:37]
	v_mfma_f32_16x16x32_bf16 v[26:29], v[154:157], v[196:199], v[26:29]
	v_mfma_f32_16x16x32_bf16 v[18:21], v[140:143], v[210:213], v[18:21]
	v_mfma_f32_16x16x32_bf16 v[10:13], v[154:157], v[210:213], v[10:13]
	s_setprio 0
	s_setprio 1
	v_mfma_f32_16x16x32_bf16 v[54:57], v[158:161], v[174:177], v[54:57]
	v_mfma_f32_16x16x32_bf16 v[46:49], v[166:169], v[174:177], v[46:49]
	v_mfma_f32_16x16x32_bf16 v[38:41], v[158:161], v[184:187], v[38:41]
	v_mfma_f32_16x16x32_bf16 v[30:33], v[166:169], v[184:187], v[30:33]
	v_mfma_f32_16x16x32_bf16 v[22:25], v[158:161], v[192:195], v[22:25]
	v_mfma_f32_16x16x32_bf16 v[14:17], v[166:169], v[192:195], v[14:17]
	v_mfma_f32_16x16x32_bf16 v[6:9], v[158:161], v[200:203], v[6:9]
	v_mfma_f32_16x16x32_bf16 v[2:5], v[166:169], v[200:203], v[2:5]
	v_mfma_f32_16x16x32_bf16 v[54:57], v[162:165], v[180:183], v[54:57]
	v_mfma_f32_16x16x32_bf16 v[46:49], v[170:173], v[180:183], v[46:49]
	v_mfma_f32_16x16x32_bf16 v[38:41], v[162:165], v[188:191], v[38:41]
	v_mfma_f32_16x16x32_bf16 v[30:33], v[170:173], v[188:191], v[30:33]
	v_mfma_f32_16x16x32_bf16 v[22:25], v[162:165], v[196:199], v[22:25]
	v_mfma_f32_16x16x32_bf16 v[14:17], v[170:173], v[196:199], v[14:17]
	v_mfma_f32_16x16x32_bf16 v[6:9], v[162:165], v[210:213], v[6:9]
	v_mfma_f32_16x16x32_bf16 v[2:5], v[170:173], v[210:213], v[2:5]
	s_barrier
	s_setprio 0
	s_add_i32 s76, s76, 2
	s_add_u32 s40, s40, 0x100
	s_addc_u32 s41, s41, 0
	s_add_u32 s68, s68, 0x100
	s_addc_u32 s69, s69, 0
	s_cmp_gt_u32 s76, 29
	s_cbranch_scc0 .LBB0_153
	s_and_b64 vcc, exec, s[48:49]
	s_cbranch_vccz .LBB0_156
	s_barrier

; #define SEAM(k) do { if (IN((k) + 1)) xcd_barrier(bar); } while (0)
; __global__ void __launch_bounds__(NWAVES * 64, 2) trunk_fwd(Args args) {
;     ...
;             SEAM(pb + 0);
;         }
;         if (IN(pb + 1) && !SKIP_ATT) {
.LBB0_218:
	s_mov_b64 s[36:37], 0x100
	s_mov_b64 s[46:47], 0x90000
	s_mov_b64 s[58:59], 0x48080
	s_mov_b64 s[60:61], 0xb0080
	v_readlane_b32 s2, v254, 38
	s_or_b32 s2, s2, 2
	v_readlane_b32 s16, v253, 5
	v_readlane_b32 s17, v253, 6
	s_cmp_le_i32 s16, s2
	s_cselect_b64 s[12:13], -1, 0
	s_cmp_lt_i32 s2, s17
	s_cselect_b64 s[16:17], -1, 0
	s_and_b64 s[12:13], s[12:13], s[16:17]
	s_andn2_b64 vcc, exec, s[12:13]
	s_cbranch_vccnz .LBB0_230
	s_waitcnt vmcnt(0)
	s_waitcnt vmcnt(0)
	s_barrier
	s_mov_b64 s[16:17], exec
	v_readlane_b32 s12, v253, 7
	v_readlane_b32 s13, v253, 8
	s_and_b64 s[12:13], s[16:17], s[12:13]
	s_mov_b32 s45, 0xf800000
	s_mov_b64 s[86:87], 0x4000400
	s_mov_b64 s[88:89], 0x4000800
	s_mov_b64 exec, s[12:13]
	s_cbranch_execz .LBB0_272
	v_readlane_b32 s3, v254, 24
	s_waitcnt vmcnt(0) expcnt(0) lgkmcnt(0)
	s_nop 0
	v_mov_b32_e32 v2, s3
	ds_read_b32 v4, v2
	v_readlane_b32 s3, v254, 25
	s_waitcnt lgkmcnt(0)
	v_cmp_ne_u32_e32 vcc, 0, v4
	v_mov_b32_e32 v2, s3
	ds_read_b32 v2, v2
	s_cbranch_vccnz .LBB0_236
	v_readlane_b32 s18, v253, 0
	v_readlane_b32 s19, v253, 1
	s_load_dwordx2 s[12:13], s[18:19], 0x4
	v_readlane_b32 s3, v253, 2
	s_mov_b32 s10, 1
	s_waitcnt lgkmcnt(0)
	s_mul_i32 s3, s12, s3
	s_mul_i32 s3, s3, s13
	s_branch .LBB0_223

; #define PG8_SB(B) __builtin_amdgcn_rcpf(1.f + expneg(B))
; #define PG8_SB(B) __builtin_amdgcn_rcpf(1.f + expneg(B))
; #define PG8_STAGE(bufoff, gbase, voff) do { _Pragma("unroll") for (int _i = 0; _i < 2; ++_i) \
;         __builtin_amdgcn_global_load_lds((const unsigned*)((const char*)(gbase) + (size_t)_i * qstep + (voff)[0]), (PG8_LAS unsigned*)(lds + (bufoff) + ldsw + _i * 8192), 16, 0, 0); } while (0)
; #define PG8_LDA(dst, b, h) do { _Pragma("unroll") for (int m = 0; m < 4; ++m) _Pragma("unroll") for (int k = 0; k < 2; ++k) dst[m][k] = *(const PG8_LAS bf16x8*)(lds + PG8_SA(b, h) + aoff + m * 2048 + k * 1024); } while (0)
; #define PG8_LDB(dst, b, h) do { _Pragma("unroll") for (int n = 0; n < 2; ++n) _Pragma("unroll") for (int k = 0; k < 2; ++k) dst[n][k] = *(const PG8_LAS bf16x8*)(lds + PG8_SB(b, h) + boff + n * 2048 + k * 1024); } while (0)
; #define PG8_WAIT_V89() do { if constexpr (SLIVER) PG8_WAIT_V(9); else PG8_WAIT_V(8); } while (0)
; #define PG8_WAIT_L(n) asm volatile("s_waitcnt lgkmcnt(" #n ")" ::: "memory")
; #define PG8_BAR __builtin_amdgcn_s_barrier()
; template <class Epi, class Sched, bool ALIGN_EPI = false, bool SP2 = false, bool SLIVER = false>
; __device__ __forceinline__ void gemm_phase(PG8_LAS unsigned char* lds, const Gemm g, const Sched& S, const Epi& E) {
;     ...
;             const bool last = (t == nt - 2);
;             const char* a1 = cA + (size_t)(t + 1) * kstep;
;             const char* a2 = last ? nA : cA + (size_t)(t + 2) * kstep; const char* b2 = last ? nB : cB + (size_t)(t + 2) * kstep;
;             const char* a3 = a2 + kstep; const char* b3 = b2 + kstep;
;             const char* s1 = cS + (size_t)(t + 1) * kstep; const char* s2 = last ? nS : cS + (size_t)(t + 2) * kstep;
;             if (last && has_next) S.a_ready(nxt);
;             if constexpr (SP2) {
;             PG8_LDB(B0, 0, 0); PG8_LDB(B1, 0, 1); PG8_SCHED; PG8_LDA(At, 0, 0); PG8_STAGE(PG8_SA(1, 1), a1 + hstep, voffA); PG8_STAGE_S(1, s1);
;             PG8_WAIT_V89(); PG8_WAIT_L(0); PG8_BAR; PG8_MMA(0, 0, At, B0); PG8_MMA(0, 1, At, B1); PG8_BAR; PG8_SCHED;
;             PG8_LDA(At, 0, 1); PG8_LDS_S(0); PG8_STAGE(PG8_SB(0, 0), b2, voffB); PG8_STAGE(PG8_SB(0, 1), b2 + hstep, voffB); PG8_STAGE(PG8_SA(0, 0), a2, voffA);
;             PG8_WAIT_V89(); PG8_WAIT_L(0); PG8_BAR; PG8_MMA(1, 0, At, B0); PG8_MMA(1, 1, At, B1); PG8_MMA_S(); PG8_BAR; PG8_SCHED;
.LBB0_705:
	s_add_u32 s76, s62, 0xfff80080
	s_addc_u32 s77, s63, -1
	s_add_i32 s78, 0, 0x10000
	s_cmp_eq_u32 s69, 28
	s_cselect_b32 s81, s3, s77
	s_cselect_b32 s80, s51, s76
	v_add_u32_e32 v142, s78, v143
	s_cselect_b32 s77, s49, s68
	s_cselect_b32 s76, s66, s67
	s_add_i32 s79, 0, 0x14000
	ds_read_b128 v[130:133], v142
	ds_read_b128 v[138:141], v142 offset:1024
	ds_read_b128 v[148:151], v142 offset:2048
	ds_read_b128 v[152:155], v142 offset:3072
	v_add_u32_e32 v142, s79, v143
	ds_read_b128 v[156:159], v142
	ds_read_b128 v[160:163], v142 offset:1024
	ds_read_b128 v[164:167], v142 offset:2048
	ds_read_b128 v[168:171], v142 offset:3072
	s_mov_b64 s[46:47], s[62:63]
	s_add_i32 m0, s45, 0xc000
	ds_read_b128 v[172:175], v147
	ds_read_b128 v[180:183], v147 offset:1024
	ds_read_b128 v[184:187], v147 offset:2048
	ds_read_b128 v[188:191], v147 offset:3072
	ds_read_b128 v[192:195], v147 offset:4096
	ds_read_b128 v[196:199], v147 offset:5120
	ds_read_b128 v[200:203], v147 offset:6144
	ds_read_b128 v[210:213], v147 offset:7168
	global_load_lds_dwordx4 v136, s[46:47]
	s_add_i32 m0, s45, 0xe000
	s_nop 0
	s_add_u32 s36, s46, 0x40000
	s_addc_u32 s37, s47, 0
	global_load_lds_dwordx4 v136, s[36:37]
	s_cmp_eq_u32 s69, s101
	s_cbranch_scc1 .Lgup_skipw0
	s_waitcnt vmcnt(8)
.Lgup_skipw0:
	s_waitcnt lgkmcnt(0)
	s_setprio 1
	s_barrier
	v_mfma_f32_16x16x32_bf16 v[126:129], v[130:133], v[172:175], v[126:129]
	v_mfma_f32_16x16x32_bf16 v[118:121], v[148:151], v[172:175], v[118:121]
	v_mfma_f32_16x16x32_bf16 v[110:113], v[130:133], v[184:187], v[110:113]
	v_mfma_f32_16x16x32_bf16 v[102:105], v[148:151], v[184:187], v[102:105]
	v_mfma_f32_16x16x32_bf16 v[94:97], v[130:133], v[192:195], v[94:97]
	v_mfma_f32_16x16x32_bf16 v[86:89], v[148:151], v[192:195], v[86:89]
	v_mfma_f32_16x16x32_bf16 v[78:81], v[130:133], v[200:203], v[78:81]
	v_mfma_f32_16x16x32_bf16 v[70:73], v[148:151], v[200:203], v[70:73]
	v_mfma_f32_16x16x32_bf16 v[126:129], v[138:141], v[180:183], v[126:129]
	v_mfma_f32_16x16x32_bf16 v[118:121], v[152:155], v[180:183], v[118:121]
	v_mfma_f32_16x16x32_bf16 v[110:113], v[138:141], v[188:191], v[110:113]
	v_mfma_f32_16x16x32_bf16 v[102:105], v[152:155], v[188:191], v[102:105]
	v_mfma_f32_16x16x32_bf16 v[94:97], v[138:141], v[196:199], v[94:97]
	v_mfma_f32_16x16x32_bf16 v[86:89], v[152:155], v[196:199], v[86:89]
	v_mfma_f32_16x16x32_bf16 v[78:81], v[138:141], v[210:213], v[78:81]
	v_mfma_f32_16x16x32_bf16 v[70:73], v[152:155], v[210:213], v[70:73]
	s_setprio 0
	s_setprio 1
	v_mfma_f32_16x16x32_bf16 v[122:125], v[156:159], v[172:175], v[122:125]
	v_mfma_f32_16x16x32_bf16 v[114:117], v[164:167], v[172:175], v[114:117]
	v_mfma_f32_16x16x32_bf16 v[106:109], v[156:159], v[184:187], v[106:109]
	v_mfma_f32_16x16x32_bf16 v[98:101], v[164:167], v[184:187], v[98:101]
	v_mfma_f32_16x16x32_bf16 v[90:93], v[156:159], v[192:195], v[90:93]
	v_mfma_f32_16x16x32_bf16 v[82:85], v[164:167], v[192:195], v[82:85]
	v_mfma_f32_16x16x32_bf16 v[74:77], v[156:159], v[200:203], v[74:77]
	v_mfma_f32_16x16x32_bf16 v[66:69], v[164:167], v[200:203], v[66:69]
	v_mfma_f32_16x16x32_bf16 v[122:125], v[160:163], v[180:183], v[122:125]
	v_mfma_f32_16x16x32_bf16 v[114:117], v[168:171], v[180:183], v[114:117]
	v_mfma_f32_16x16x32_bf16 v[106:109], v[160:163], v[188:191], v[106:109]
	v_mfma_f32_16x16x32_bf16 v[98:101], v[168:171], v[188:191], v[98:101]
	v_mfma_f32_16x16x32_bf16 v[90:93], v[160:163], v[196:199], v[90:93]
	v_mfma_f32_16x16x32_bf16 v[82:85], v[168:171], v[196:199], v[82:85]
	v_mfma_f32_16x16x32_bf16 v[74:77], v[160:163], v[210:213], v[74:77]
	v_mfma_f32_16x16x32_bf16 v[66:69], v[168:171], v[210:213], v[66:69]
	s_barrier
	s_setprio 0
	s_mov_b64 s[46:47], s[76:77]
	s_add_i32 s76, s78, s88
	s_mov_b32 m0, s76
	ds_read_b128 v[172:175], v147 offset:16384
	ds_read_b128 v[180:183], v147 offset:17408
	ds_read_b128 v[184:187], v147 offset:18432
	ds_read_b128 v[188:191], v147 offset:19456
	ds_read_b128 v[192:195], v147 offset:20480
	ds_read_b128 v[196:199], v147 offset:21504
	ds_read_b128 v[200:203], v147 offset:22528
	ds_read_b128 v[210:213], v147 offset:23552
	global_load_lds_dwordx4 v178, s[46:47]
	s_add_i32 m0, s76, 0x2000
	s_add_i32 s76, s79, s88
	s_add_u32 s58, s46, 0x40000
	s_addc_u32 s59, s47, 0
	global_load_lds_dwordx4 v178, s[58:59]
	s_mov_b32 m0, s76
	s_nop 0
	s_add_u32 s60, s46, 0x80000
	s_addc_u32 s61, s47, 0
	global_load_lds_dwordx4 v178, s[60:61]
	s_add_i32 m0, s76, 0x2000
	s_nop 0
	s_add_u32 s36, s46, 0xc0000
	s_addc_u32 s37, s47, 0
	global_load_lds_dwordx4 v178, s[36:37]
	s_mov_b32 m0, s45
	s_nop 0
	global_load_lds_dwordx4 v134, s[80:81]
	s_mov_b32 m0, s83
	s_nop 0
	s_add_u32 s58, s80, 0x40000
	s_addc_u32 s59, s81, 0
	global_load_lds_dwordx4 v134, s[58:59]
	s_cmp_eq_u32 s69, s101
	s_cbranch_scc1 .Lgup_skipw1
	s_waitcnt vmcnt(8)
; #define PG8_STAGE(bufoff, gbase, voff) do { _Pragma("unroll") for (int _i = 0; _i < 2; ++_i) \
;         __builtin_amdgcn_global_load_lds((const unsigned*)((const char*)(gbase) + (size_t)_i * qstep + (voff)[0]), (PG8_LAS unsigned*)(lds + (bufoff) + ldsw + _i * 8192), 16, 0, 0); } while (0)
; #define PG8_LDA(dst, b, h) do { _Pragma("unroll") for (int m = 0; m < 4; ++m) _Pragma("unroll") for (int k = 0; k < 2; ++k) dst[m][k] = *(const PG8_LAS bf16x8*)(lds + PG8_SA(b, h) + aoff + m * 2048 + k * 1024); } while (0)
; #define PG8_LDB(dst, b, h) do { _Pragma("unroll") for (int n = 0; n < 2; ++n) _Pragma("unroll") for (int k = 0; k < 2; ++k) dst[n][k] = *(const PG8_LAS bf16x8*)(lds + PG8_SB(b, h) + boff + n * 2048 + k * 1024); } while (0)
; #define PG8_MMA(ai, bj, At, Bt) do { __builtin_amdgcn_s_setprio(1); _Pragma("unroll") for (int m = 0; m < 4; ++m) _Pragma("unroll") for (int n = 0; n < 2; ++n) _Pragma("unroll") for (int k = 0; k < 2; ++k) \
;         acc[ai][bj][m][n] = __builtin_amdgcn_mfma_f32_16x16x32_bf16(Bt[n][k], At[m][k], acc[ai][bj][m][n], 0, 0, 0); __builtin_amdgcn_s_setprio(0); } while (0)
; #define PG8_WAIT_V89() do { if constexpr (SLIVER) PG8_WAIT_V(9); else PG8_WAIT_V(8); } while (0)
; #define PG8_STAGE_S(b, gbase) do { if constexpr (SLIVER) __builtin_amdgcn_global_load_lds((const unsigned*)((const char*)(gbase) + voffS), (PG8_LAS unsigned*)(lds + STAGE_BYTES + (b) * 2048 + wid * 256), 4, 0, 0); } while (0)
; #define PG8_WAIT_L(n) asm volatile("s_waitcnt lgkmcnt(" #n ")" ::: "memory")
; #define PG8_BAR __builtin_amdgcn_s_barrier()
; #define PG8_SCHED __builtin_amdgcn_sched_barrier(0)
; template <class Epi, class Sched, bool ALIGN_EPI = false, bool SP2 = false, bool SLIVER = false>
; __device__ __forceinline__ void gemm_phase(PG8_LAS unsigned char* lds, const Gemm g, const Sched& S, const Epi& E) {
;     ...
;             PG8_WAIT_V89(); PG8_WAIT_L(0); PG8_BAR; PG8_MMA(1, 0, At, B0); PG8_MMA(1, 1, At, B1); PG8_MMA_S(); PG8_BAR; PG8_SCHED;
;             PG8_LDB(B0, 1, 0); PG8_LDB(B1, 1, 1); PG8_SCHED; PG8_LDA(At, 1, 0); PG8_STAGE(PG8_SA(0, 1), a2 + hstep, voffA); PG8_STAGE_S(0, s2);
;             PG8_WAIT_V89(); PG8_WAIT_L(0); PG8_BAR; PG8_MMA(0, 0, At, B0); PG8_MMA(0, 1, At, B1); PG8_BAR; PG8_SCHED;
.Lgup_skipw1:
	s_waitcnt lgkmcnt(0)
	s_setprio 1
	s_barrier
	v_mfma_f32_16x16x32_bf16 v[62:65], v[130:133], v[172:175], v[62:65]
	v_mfma_f32_16x16x32_bf16 v[54:57], v[148:151], v[172:175], v[54:57]
	v_mfma_f32_16x16x32_bf16 v[46:49], v[130:133], v[184:187], v[46:49]
	v_mfma_f32_16x16x32_bf16 v[38:41], v[148:151], v[184:187], v[38:41]
	v_mfma_f32_16x16x32_bf16 v[30:33], v[130:133], v[192:195], v[30:33]
	v_mfma_f32_16x16x32_bf16 v[22:25], v[148:151], v[192:195], v[22:25]
	v_mfma_f32_16x16x32_bf16 v[14:17], v[130:133], v[200:203], v[14:17]
	v_mfma_f32_16x16x32_bf16 v[6:9], v[148:151], v[200:203], v[6:9]
	v_mfma_f32_16x16x32_bf16 v[62:65], v[138:141], v[180:183], v[62:65]
	v_mfma_f32_16x16x32_bf16 v[54:57], v[152:155], v[180:183], v[54:57]
	v_mfma_f32_16x16x32_bf16 v[46:49], v[138:141], v[188:191], v[46:49]
	v_mfma_f32_16x16x32_bf16 v[38:41], v[152:155], v[188:191], v[38:41]
	v_mfma_f32_16x16x32_bf16 v[30:33], v[138:141], v[196:199], v[30:33]
	v_mfma_f32_16x16x32_bf16 v[22:25], v[152:155], v[196:199], v[22:25]
	v_mfma_f32_16x16x32_bf16 v[14:17], v[138:141], v[210:213], v[14:17]
	v_mfma_f32_16x16x32_bf16 v[6:9], v[152:155], v[210:213], v[6:9]
	s_setprio 0
	s_setprio 1
	v_mfma_f32_16x16x32_bf16 v[58:61], v[156:159], v[172:175], v[58:61]
	v_mfma_f32_16x16x32_bf16 v[50:53], v[164:167], v[172:175], v[50:53]
	v_mfma_f32_16x16x32_bf16 v[42:45], v[156:159], v[184:187], v[42:45]
	v_mfma_f32_16x16x32_bf16 v[34:37], v[164:167], v[184:187], v[34:37]
	v_mfma_f32_16x16x32_bf16 v[26:29], v[156:159], v[192:195], v[26:29]
	v_mfma_f32_16x16x32_bf16 v[18:21], v[164:167], v[192:195], v[18:21]
	v_mfma_f32_16x16x32_bf16 v[10:13], v[156:159], v[200:203], v[10:13]
	v_mfma_f32_16x16x32_bf16 v[2:5], v[164:167], v[200:203], v[2:5]
	v_mfma_f32_16x16x32_bf16 v[58:61], v[160:163], v[180:183], v[58:61]
	v_mfma_f32_16x16x32_bf16 v[50:53], v[168:171], v[180:183], v[50:53]
	v_mfma_f32_16x16x32_bf16 v[42:45], v[160:163], v[188:191], v[42:45]
	v_mfma_f32_16x16x32_bf16 v[34:37], v[168:171], v[188:191], v[34:37]
	v_mfma_f32_16x16x32_bf16 v[26:29], v[160:163], v[196:199], v[26:29]
	v_mfma_f32_16x16x32_bf16 v[18:21], v[168:171], v[196:199], v[18:21]
	v_mfma_f32_16x16x32_bf16 v[10:13], v[160:163], v[210:213], v[10:13]
	v_mfma_f32_16x16x32_bf16 v[2:5], v[168:171], v[210:213], v[2:5]
	s_barrier
	s_setprio 0
	s_add_i32 s76, 0, 0x18000
	v_add_u32_e32 v142, s76, v143
	s_add_i32 s77, 0, 0x1c000
	ds_read_b128 v[130:133], v142
	ds_read_b128 v[138:141], v142 offset:1024
	ds_read_b128 v[148:151], v142 offset:2048
	ds_read_b128 v[152:155], v142 offset:3072
	v_add_u32_e32 v142, s77, v143
	ds_read_b128 v[156:159], v142
	ds_read_b128 v[160:163], v142 offset:1024
	ds_read_b128 v[164:167], v142 offset:2048
	ds_read_b128 v[168:171], v142 offset:3072
	s_mov_b32 m0, s90
	ds_read_b128 v[172:175], v147 offset:32768
	ds_read_b128 v[180:183], v147 offset:33792
	ds_read_b128 v[184:187], v147 offset:34816
	ds_read_b128 v[188:191], v147 offset:35840
	ds_read_b128 v[192:195], v147 offset:36864
	ds_read_b128 v[196:199], v147 offset:37888
	ds_read_b128 v[200:203], v147 offset:38912
	ds_read_b128 v[210:213], v147 offset:39936
	s_add_u32 s60, s80, 0x80000
	s_addc_u32 s61, s81, 0
	global_load_lds_dwordx4 v134, s[60:61]
	s_mov_b32 m0, s91
	s_nop 0
	s_add_u32 s36, s80, 0xc0000
	s_addc_u32 s37, s81, 0
	global_load_lds_dwordx4 v134, s[36:37]
	s_waitcnt vmcnt(8)
	s_waitcnt lgkmcnt(0)
	s_setprio 1
	s_barrier
	v_mfma_f32_16x16x32_bf16 v[126:129], v[130:133], v[172:175], v[126:129]
	v_mfma_f32_16x16x32_bf16 v[118:121], v[148:151], v[172:175], v[118:121]
	v_mfma_f32_16x16x32_bf16 v[110:113], v[130:133], v[184:187], v[110:113]
	v_mfma_f32_16x16x32_bf16 v[102:105], v[148:151], v[184:187], v[102:105]
	v_mfma_f32_16x16x32_bf16 v[94:97], v[130:133], v[192:195], v[94:97]
	v_mfma_f32_16x16x32_bf16 v[86:89], v[148:151], v[192:195], v[86:89]
	v_mfma_f32_16x16x32_bf16 v[78:81], v[130:133], v[200:203], v[78:81]
	v_mfma_f32_16x16x32_bf16 v[70:73], v[148:151], v[200:203], v[70:73]
	v_mfma_f32_16x16x32_bf16 v[126:129], v[138:141], v[180:183], v[126:129]
	v_mfma_f32_16x16x32_bf16 v[118:121], v[152:155], v[180:183], v[118:121]
	v_mfma_f32_16x16x32_bf16 v[110:113], v[138:141], v[188:191], v[110:113]
	v_mfma_f32_16x16x32_bf16 v[102:105], v[152:155], v[188:191], v[102:105]
	v_mfma_f32_16x16x32_bf16 v[94:97], v[138:141], v[196:199], v[94:97]
	v_mfma_f32_16x16x32_bf16 v[86:89], v[152:155], v[196:199], v[86:89]
	v_mfma_f32_16x16x32_bf16 v[78:81], v[138:141], v[210:213], v[78:81]
	v_mfma_f32_16x16x32_bf16 v[70:73], v[152:155], v[210:213], v[70:73]
	s_setprio 0
	s_setprio 1
	v_mfma_f32_16x16x32_bf16 v[122:125], v[156:159], v[172:175], v[122:125]
	v_mfma_f32_16x16x32_bf16 v[114:117], v[164:167], v[172:175], v[114:117]
	v_mfma_f32_16x16x32_bf16 v[106:109], v[156:159], v[184:187], v[106:109]
	v_mfma_f32_16x16x32_bf16 v[98:101], v[164:167], v[184:187], v[98:101]
	v_mfma_f32_16x16x32_bf16 v[90:93], v[156:159], v[192:195], v[90:93]
	v_mfma_f32_16x16x32_bf16 v[82:85], v[164:167], v[192:195], v[82:85]
	v_mfma_f32_16x16x32_bf16 v[74:77], v[156:159], v[200:203], v[74:77]
	v_mfma_f32_16x16x32_bf16 v[66:69], v[164:167], v[200:203], v[66:69]
	v_mfma_f32_16x16x32_bf16 v[122:125], v[160:163], v[180:183], v[122:125]
	v_mfma_f32_16x16x32_bf16 v[114:117], v[168:171], v[180:183], v[114:117]
	v_mfma_f32_16x16x32_bf16 v[106:109], v[160:163], v[188:191], v[106:109]
	v_mfma_f32_16x16x32_bf16 v[98:101], v[168:171], v[188:191], v[98:101]
	v_mfma_f32_16x16x32_bf16 v[90:93], v[160:163], v[196:199], v[90:93]
	v_mfma_f32_16x16x32_bf16 v[82:85], v[168:171], v[196:199], v[82:85]
	v_mfma_f32_16x16x32_bf16 v[74:77], v[160:163], v[210:213], v[74:77]
	v_mfma_f32_16x16x32_bf16 v[66:69], v[168:171], v[210:213], v[66:69]
	s_barrier
; #define PG8_SB(B) __builtin_amdgcn_rcpf(1.f + expneg(B))
; #define PG8_SB(B) __builtin_amdgcn_rcpf(1.f + expneg(B))
; #define PG8_STAGE(bufoff, gbase, voff) do { _Pragma("unroll") for (int _i = 0; _i < 2; ++_i) \
;         __builtin_amdgcn_global_load_lds((const unsigned*)((const char*)(gbase) + (size_t)_i * qstep + (voff)[0]), (PG8_LAS unsigned*)(lds + (bufoff) + ldsw + _i * 8192), 16, 0, 0); } while (0)
; #define PG8_LDA(dst, b, h) do { _Pragma("unroll") for (int m = 0; m < 4; ++m) _Pragma("unroll") for (int k = 0; k < 2; ++k) dst[m][k] = *(const PG8_LAS bf16x8*)(lds + PG8_SA(b, h) + aoff + m * 2048 + k * 1024); } while (0)
; #define PG8_MMA(ai, bj, At, Bt) do { __builtin_amdgcn_s_setprio(1); _Pragma("unroll") for (int m = 0; m < 4; ++m) _Pragma("unroll") for (int n = 0; n < 2; ++n) _Pragma("unroll") for (int k = 0; k < 2; ++k) \
;         acc[ai][bj][m][n] = __builtin_amdgcn_mfma_f32_16x16x32_bf16(Bt[n][k], At[m][k], acc[ai][bj][m][n], 0, 0, 0); __builtin_amdgcn_s_setprio(0); } while (0)
; #define PG8_WAIT_V89() do { if constexpr (SLIVER) PG8_WAIT_V(9); else PG8_WAIT_V(8); } while (0)
; #define PG8_LDS_S(b) do { if constexpr (SLIVER) { Sf[0] = *(const PG8_LAS bf16x8*)(lds + STAGE_BYTES + (b) * 2048 + soff0); Sf[1] = *(const PG8_LAS bf16x8*)(lds + STAGE_BYTES + (b) * 2048 + (soff0 ^ 64)); } } while (0)
; #define PG8_WAIT_L(n) asm volatile("s_waitcnt lgkmcnt(" #n ")" ::: "memory")
; #define PG8_BAR __builtin_amdgcn_s_barrier()
; #define PG8_SCHED __builtin_amdgcn_sched_barrier(0)
; template <class Epi, class Sched, bool ALIGN_EPI = false, bool SP2 = false, bool SLIVER = false>
; __device__ __forceinline__ void gemm_phase(PG8_LAS unsigned char* lds, const Gemm g, const Sched& S, const Epi& E) {
;     ...
;             PG8_LDA(At, 1, 1); PG8_LDS_S(1); PG8_STAGE(PG8_SB(1, 0), b3, voffB); PG8_STAGE(PG8_SB(1, 1), b3 + hstep, voffB); PG8_STAGE(PG8_SA(1, 0), a3, voffA);
;             PG8_WAIT_V89(); PG8_WAIT_L(0); PG8_BAR; PG8_MMA(1, 0, At, B0); PG8_MMA(1, 1, At, B1); PG8_MMA_S(); PG8_BAR; PG8_SCHED;
;     ...
;         if constexpr (ALIGN_EPI) { if (wr == 0) PG8_BAR; }
	s_setprio 0
	s_add_i32 s76, s76, s88
	s_mov_b32 m0, s76
	ds_read_b128 v[172:175], v147 offset:49152
	ds_read_b128 v[180:183], v147 offset:50176
	ds_read_b128 v[184:187], v147 offset:51200
	ds_read_b128 v[188:191], v147 offset:52224
	ds_read_b128 v[192:195], v147 offset:53248
	ds_read_b128 v[196:199], v147 offset:54272
	ds_read_b128 v[200:203], v147 offset:55296
	ds_read_b128 v[210:213], v147 offset:56320
	s_add_u32 s58, s46, 0x80
	s_addc_u32 s59, s47, 0
	global_load_lds_dwordx4 v178, s[58:59]
	s_add_i32 m0, s76, 0x2000
	s_add_i32 s76, s77, s88
	s_add_u32 s60, s46, 0x40080
	s_addc_u32 s61, s47, 0
	global_load_lds_dwordx4 v178, s[60:61]
	s_mov_b32 m0, s76
	s_add_u32 s36, s46, 0x80080
	s_addc_u32 s37, s47, 0
	global_load_lds_dwordx4 v178, s[36:37]
	s_add_i32 m0, s76, 0x2000
	s_nop 0
	s_add_u32 s58, s46, 0xc0080
	s_addc_u32 s59, s47, 0
	global_load_lds_dwordx4 v178, s[58:59]
	s_mov_b32 m0, s93
	s_nop 0
	s_add_u32 s60, s80, 0x80
	s_addc_u32 s61, s81, 0
	global_load_lds_dwordx4 v134, s[60:61]
	s_mov_b32 m0, s94
	s_nop 0
	s_add_u32 s36, s80, 0x40080
	s_addc_u32 s37, s81, 0
	global_load_lds_dwordx4 v134, s[36:37]
	s_waitcnt vmcnt(8)
	s_waitcnt lgkmcnt(0)
	s_setprio 1
	s_barrier
	v_mfma_f32_16x16x32_bf16 v[62:65], v[130:133], v[172:175], v[62:65]
	v_mfma_f32_16x16x32_bf16 v[54:57], v[148:151], v[172:175], v[54:57]
	v_mfma_f32_16x16x32_bf16 v[46:49], v[130:133], v[184:187], v[46:49]
	v_mfma_f32_16x16x32_bf16 v[38:41], v[148:151], v[184:187], v[38:41]
	v_mfma_f32_16x16x32_bf16 v[30:33], v[130:133], v[192:195], v[30:33]
	v_mfma_f32_16x16x32_bf16 v[22:25], v[148:151], v[192:195], v[22:25]
	v_mfma_f32_16x16x32_bf16 v[14:17], v[130:133], v[200:203], v[14:17]
	v_mfma_f32_16x16x32_bf16 v[6:9], v[148:151], v[200:203], v[6:9]
	v_mfma_f32_16x16x32_bf16 v[62:65], v[138:141], v[180:183], v[62:65]
	v_mfma_f32_16x16x32_bf16 v[54:57], v[152:155], v[180:183], v[54:57]
	v_mfma_f32_16x16x32_bf16 v[46:49], v[138:141], v[188:191], v[46:49]
	v_mfma_f32_16x16x32_bf16 v[38:41], v[152:155], v[188:191], v[38:41]
	v_mfma_f32_16x16x32_bf16 v[30:33], v[138:141], v[196:199], v[30:33]
	v_mfma_f32_16x16x32_bf16 v[22:25], v[152:155], v[196:199], v[22:25]
	v_mfma_f32_16x16x32_bf16 v[14:17], v[138:141], v[210:213], v[14:17]
	v_mfma_f32_16x16x32_bf16 v[6:9], v[152:155], v[210:213], v[6:9]
	s_setprio 0
	s_setprio 1
	v_mfma_f32_16x16x32_bf16 v[58:61], v[156:159], v[172:175], v[58:61]
	v_mfma_f32_16x16x32_bf16 v[50:53], v[164:167], v[172:175], v[50:53]
	v_mfma_f32_16x16x32_bf16 v[42:45], v[156:159], v[184:187], v[42:45]
	v_mfma_f32_16x16x32_bf16 v[34:37], v[164:167], v[184:187], v[34:37]
	v_mfma_f32_16x16x32_bf16 v[26:29], v[156:159], v[192:195], v[26:29]
	v_mfma_f32_16x16x32_bf16 v[18:21], v[164:167], v[192:195], v[18:21]
	v_mfma_f32_16x16x32_bf16 v[10:13], v[156:159], v[200:203], v[10:13]
	v_mfma_f32_16x16x32_bf16 v[2:5], v[164:167], v[200:203], v[2:5]
	v_mfma_f32_16x16x32_bf16 v[58:61], v[160:163], v[180:183], v[58:61]
	v_mfma_f32_16x16x32_bf16 v[50:53], v[168:171], v[180:183], v[50:53]
	v_mfma_f32_16x16x32_bf16 v[42:45], v[160:163], v[188:191], v[42:45]
	v_mfma_f32_16x16x32_bf16 v[34:37], v[168:171], v[188:191], v[34:37]
	v_mfma_f32_16x16x32_bf16 v[26:29], v[160:163], v[196:199], v[26:29]
	v_mfma_f32_16x16x32_bf16 v[18:21], v[168:171], v[196:199], v[18:21]
	v_mfma_f32_16x16x32_bf16 v[10:13], v[160:163], v[210:213], v[10:13]
	v_mfma_f32_16x16x32_bf16 v[2:5], v[168:171], v[210:213], v[2:5]
	s_barrier
	s_setprio 0
	s_add_i32 s69, s69, 2
	s_add_u32 s62, s62, 0x100
	s_addc_u32 s63, s63, 0
	s_add_u32 s67, s67, 0x100
	s_addc_u32 s68, s68, 0
	s_cmp_gt_u32 s69, 29
	s_cbranch_scc0 .LBB0_705
	s_and_b64 vcc, exec, s[42:43]
	s_cbranch_vccz .LBB0_708
	s_barrier

; #define SEAM(k) do { if (IN((k) + 1)) xcd_barrier(bar); } while (0)
; __global__ void __launch_bounds__(NWAVES * 64, 2) trunk_fwd(Args args) {
;     ...
;             SEAM(pb + 5);
;         }
;         if (IN(pb + 6) && !SKIP_GDN) {
.LBB0_730:
	s_mov_b64 s[36:37], 0x100
	s_mov_b64 s[46:47], 0x90000
	s_mov_b64 s[58:59], 0x48080
	s_mov_b64 s[60:61], 0xb0080
	v_readlane_b32 s2, v254, 38
	s_or_b32 s2, s2, 7
	v_readlane_b32 s16, v253, 5
	v_readlane_b32 s17, v253, 6
	s_cmp_le_i32 s16, s2
	s_cselect_b64 s[12:13], -1, 0
	s_cmp_lt_i32 s2, s17
	s_cselect_b64 s[16:17], -1, 0
	s_and_b64 s[12:13], s[12:13], s[16:17]
	s_andn2_b64 vcc, exec, s[12:13]
	s_cbranch_vccnz .LBB0_784
	s_waitcnt vmcnt(0)
	s_waitcnt vmcnt(0) lgkmcnt(0)
	s_barrier
	s_mov_b64 s[16:17], exec
	v_readlane_b32 s12, v253, 7
	v_readlane_b32 s13, v253, 8
	s_and_b64 s[12:13], s[16:17], s[12:13]
	s_mov_b64 exec, s[12:13]
	s_cbranch_execz .LBB0_783
	v_readlane_b32 s3, v254, 24
	s_waitcnt vmcnt(0) expcnt(0) lgkmcnt(0)
	s_nop 0
	v_mov_b32_e32 v2, s3
	ds_read_b32 v4, v2
	v_readlane_b32 s3, v254, 25
	s_waitcnt lgkmcnt(0)
	v_cmp_ne_u32_e32 vcc, 0, v4
	v_mov_b32_e32 v2, s3
	ds_read_b32 v2, v2
	s_cbranch_vccnz .LBB0_747
	v_readlane_b32 s18, v253, 0
	v_readlane_b32 s19, v253, 1
	s_load_dwordx2 s[12:13], s[18:19], 0x4
	v_readlane_b32 s3, v253, 2
	s_mov_b32 s10, 1
	s_waitcnt lgkmcnt(0)
	s_mul_i32 s3, s12, s3
	s_mul_i32 s3, s3, s13
	s_branch .LBB0_735
